# v40 plus back-edge rotation in the attention main loop: taken branch moved before the per-tile barrier
# baseline (speedup 1.0000x reference)
; __device__ __forceinline__ int otid() { int t = threadIdx.x; asm volatile("" : "+v"(t)); return t; }
; #define WAIT_BAR(N) asm volatile("s_waitcnt vmcnt(" #N ") lgkmcnt(0)\n\ts_barrier":::"memory")
;   #define DMA_K(t,slot) glds16(ksrc+(long)(t)*KVBLK*KVP,(unsigned)__builtin_amdgcn_readfirstlane(kdst+(slot)))
;   #define DMA_V(t,slot) glds16(vsrc+(long)(t)*KVBLK*KVP,(unsigned)__builtin_amdgcn_readfirstlane(vdst+(slot)))
;   #define CMASK(P0,P1,t) do{}while(0)
;   #define CMASK(P0,P1,t) do{}while(0)
;   #define CMASK(P0,P1,t) do{}while(0)
; template<int THRL> __device__ __forceinline__ void attn_unit(const bf16*Qu,const bf16*__restrict__ Kh,const bf16*__restrict__ Vh,bf16*Ou,const int NT,const float shift,char*shm){
;   const int tid=otid(),lane=tid&63,r32=lane&31,hi=lane>>5; const int wid=__builtin_amdgcn_readfirstlane(tid>>6);
;   const bf16*Qw=Qu+(long)wid*QBLK*QP;
;   const unsigned lds0=(unsigned)(uintptr_t)shm;
;   float*wsf=(float*)(shm+LDS_WS)+wid*64;
;   const bf16*ksrc=Kh+(long)lane*KVP+wid*8;
;   const bf16*vsrc=Vh+(long)(16*(wid&3)+(lane>>2))*KVP+(wid>>2)*32+(lane&3)*8;
;   const unsigned kdst=lds0+LDS_K+wid*1024, vdst=lds0+LDS_V+wid*1024;
;     ...
;   const int vb0=(int)(lds0+LDS_V)+((lane>>4)&1)*32+(lane&3)*8+(4*hi+((lane&15)>>2))*64;
;   const char*Kbase=shm+LDS_K; bf16x8 kf[8];
;   const lds_cptr shm3=(lds_cptr)shm; const lds_cptr kp0=shm3+LDS_K+hi*1024+r32*16; const lds_cptr vp0=shm3+LDS_V+((lane>>4)&1)*32+(lane&3)*8+(4*hi+((lane&15)>>2))*64;
;   DMA_K(0,0);DMA_V(0,0);DMA_K(1,SLOTB);
;   bf16x8 qr[4];
;   #pragma unroll
;   for(int d0=0;d0<4;++d0)qr[d0]=*reinterpret_cast<const bf16x8*>(&Qw[(long)r32*QP+d0*16+hi*8]);
;   float mhat=0.f,l_reg=0.f;f32x16 o[2];o[0]=f32x16{};o[1]=f32x16{};f32x16 negm=f32x16{};asm volatile("":"+v"(negm));
;     ...
;   bool resc=false;
;     ...
;   f32x16 pA0,pA1,pB0,pB1;
;   int sl_prev=0,sl_cur=0,sl_next=SLOTB;
;     ...
;   DMA_K(2,2*SLOTB);
;   WAIT_BAR(3);
;   qkt(pA0,pA1,Kbase,qr,negm,r32,hi);asm volatile("s_nop 15\n\ts_nop 7":"+v"(pA0),"+v"(pA1));CMASK(pA0,pA1,0);
;   START(pA0,pA1);
;   _Pragma("unroll") for(int r=0;r<16;++r)pA1[r]=__builtin_amdgcn_exp2f(pA1[r]);
;   WAIT_BAR(0);
.LBB0_616:
	s_lshl_b32 s4, s84, 1
	s_ashr_i32 s5, s82, 2
	s_add_i32 s6, s4, s5
	v_readlane_b32 s4, v246, 62
	v_readlane_b32 s5, v246, 63
	s_lshl_b64 s[4:5], s[4:5], 11
	s_add_u32 s7, s57, s4
	s_addc_u32 s24, s58, s5
	s_lshl_b32 s4, s82, 6
	s_ashr_i32 s5, s4, 31
	s_lshl_b64 s[48:49], s[4:5], 1
	s_add_u32 s26, s7, s48
	s_addc_u32 s27, s24, s49
	s_mul_hi_i32 s7, s6, 0x208000
	s_mul_i32 s6, s6, 0x208000
	s_add_u32 s4, s59, s6
	s_addc_u32 s5, s60, s7
	v_mov_b32_e32 v42, v216
	s_add_u32 s6, s61, s6
	s_addc_u32 s7, s62, s7
	v_readfirstlane_b32 s69, v42
	s_ashr_i32 s44, s69, 6
	s_ashr_i32 s45, s44, 31
	v_and_b32_e32 v238, 63, v42
	s_lshl_b64 s[24:25], s[44:45], 16
	s_add_u32 s24, s26, s24
	v_lshlrev_b32_e32 v0, 4, v42
	s_addc_u32 s25, s27, s25
	v_lshl_add_u64 v[2:3], s[4:5], 0, v[0:1]
	s_mov_b32 s4, 0
	s_ashr_i32 s5, s4, 31
	v_lshl_add_u64 v[212:213], s[4:5], 1, v[2:3]
	s_lshl_b32 s4, s44, 4
	v_bfe_u32 v0, v42, 2, 4
	v_and_or_b32 v0, s4, 48, v0
	s_ashr_i32 s4, s69, 3
	s_andn2_b32 s4, s4, 31
	v_lshlrev_b32_e32 v0, 7, v0
	s_ashr_i32 s5, s4, 31
	s_lshl_b32 s70, s44, 10
	v_lshl_add_u64 v[2:3], s[6:7], 0, v[0:1]
	v_lshlrev_b32_e32 v239, 3, v42
	s_cmp_lg_u32 0, -1
	v_lshl_add_u64 v[2:3], s[4:5], 1, v[2:3]
	v_and_b32_e32 v242, 24, v239
	s_cselect_b32 s4, 0, 0
	v_and_b32_e32 v240, 31, v42
	v_lshlrev_b32_e32 v0, 4, v42
	s_add_i32 s70, s70, s4
	s_mov_b32 s4, m0
	s_mov_b32 m0, s70
	s_nop 0
	global_load_lds_dwordx4 v[212:213], off
	s_mov_b32 m0, s4
	v_bfe_u32 v241, v42, 5, 1
	v_lshl_add_u64 v[214:215], s[6:7], 0, v[0:1]
	s_add_i32 s71, s70, 0x6000
	s_mov_b32 s4, m0
	s_mov_b32 m0, s71
	s_nop 0
	global_load_lds_dwordx4 v[214:215], off
	s_mov_b32 m0, s4
	s_mov_b64 s[26:27], 0x2000
	v_lshlrev_b32_e32 v0, 11, v240
	v_lshl_add_u64 v[2:3], v[212:213], 0, s[26:27]
	s_add_i32 s4, s70, 0x2000
	s_mov_b32 s5, m0
	s_mov_b32 m0, s4
	s_nop 0
	global_load_lds_dwordx4 v[2:3], off
	s_mov_b32 m0, s5
	v_lshl_or_b32 v0, v241, 4, v0
	global_load_dwordx4 v[150:153], v0, s[24:25]
	global_load_dwordx4 v[138:141], v0, s[24:25] offset:32
	global_load_dwordx4 v[134:137], v0, s[24:25] offset:64
	global_load_dwordx4 v[130:133], v0, s[24:25] offset:96
	v_mov_b32_e32 v2, v1
	v_mov_b32_e32 v3, v1
	v_mov_b32_e32 v4, v1
	v_mov_b32_e32 v5, v1
	v_mov_b32_e32 v6, v1
	v_mov_b32_e32 v7, v1
	v_mov_b32_e32 v8, v1
	v_mov_b32_e32 v9, v1
	v_mov_b32_e32 v10, v1
	v_mov_b32_e32 v11, v1
	v_mov_b32_e32 v12, v1
	v_mov_b32_e32 v13, v1
	v_mov_b32_e32 v14, v1
	v_mov_b32_e32 v15, v1
	v_lshlrev_b32_e32 v0, 10, v241
	v_lshlrev_b32_e32 v16, 4, v240
	v_add3_u32 v244, 0, v0, v16
	v_mov_b32_e32 v0, v1
	v_mov_b64_e32 v[16:17], v[14:15]
	v_mov_b64_e32 v[14:15], v[12:13]
	v_mov_b64_e32 v[12:13], v[10:11]
	v_mov_b64_e32 v[10:11], v[8:9]
	v_mov_b64_e32 v[8:9], v[6:7]
	v_mov_b64_e32 v[6:7], v[4:5]
	v_mov_b64_e32 v[4:5], v[2:3]
	v_mov_b64_e32 v[2:3], v[0:1]
	v_lshl_add_u64 v[18:19], v[212:213], 0, s[72:73]
	s_add_i32 s4, s70, 0x4000
	s_mov_b32 s5, m0
	s_mov_b32 m0, s4
	s_nop 0
	global_load_lds_dwordx4 v[18:19], off
	s_mov_b32 m0, s5
	s_waitcnt vmcnt(3) lgkmcnt(0)
	s_barrier
	ds_read_b128 v[34:37], v244
	ds_read_b128 v[38:41], v244 offset:512
	v_lshlrev_b32_e32 v0, 1, v42
	v_and_b32_e32 v243, 32, v0
	s_mov_b64 s[34:35], 0x6000
	v_add_u32_e32 v50, 0, v243
	s_mov_b32 s5, 1
	s_mov_b32 s4, 0
	s_movk_i32 s31, 0x2000
	s_mov_b32 s24, 0
	s_movk_i32 s76, 0x4000
	s_waitcnt vmcnt(3) lgkmcnt(1)
	v_mfma_f32_32x32x16_bf16 v[18:33], v[34:37], v[150:153], v[2:17]
	s_waitcnt lgkmcnt(0)
	v_mfma_f32_32x32x16_bf16 v[2:17], v[38:41], v[150:153], v[2:17]
	ds_read_b128 v[34:37], v244 offset:2048
	ds_read_b128 v[38:41], v244 offset:2560
	s_waitcnt vmcnt(2) lgkmcnt(1)
	v_mfma_f32_32x32x16_bf16 v[18:33], v[34:37], v[138:141], v[18:33]
	s_waitcnt lgkmcnt(0)
	v_mfma_f32_32x32x16_bf16 v[2:17], v[38:41], v[138:141], v[2:17]
	ds_read_b128 v[34:37], v244 offset:4096
	ds_read_b128 v[38:41], v244 offset:4608
	s_waitcnt vmcnt(1) lgkmcnt(1)
	v_mfma_f32_32x32x16_bf16 v[18:33], v[34:37], v[134:137], v[18:33]
	ds_read_b128 v[34:37], v244 offset:6144
	s_waitcnt lgkmcnt(1)
	v_mfma_f32_32x32x16_bf16 v[2:17], v[38:41], v[134:137], v[2:17]
	ds_read_b128 v[38:41], v244 offset:6656
	s_waitcnt vmcnt(0) lgkmcnt(1)
	v_mfma_f32_32x32x16_bf16 v[18:33], v[34:37], v[130:133], v[18:33]
	v_add_f32_e32 v34, v1, v237
	v_lshlrev_b32_e32 v35, 4, v42
	v_xor_b32_e32 v34, 0x80000000, v34
	v_and_b32_e32 v0, 0xc0, v35
	v_mov_b32_e32 v35, v34
	v_mov_b32_e32 v36, v34
	v_mov_b32_e32 v37, v34
	s_waitcnt lgkmcnt(0)
	v_mfma_f32_32x32x16_bf16 v[2:17], v[38:41], v[130:133], v[2:17]
	s_nop 15
	s_nop 7
	v_mov_b32_e32 v38, v34
	v_mov_b32_e32 v39, v34
	v_mov_b32_e32 v40, v34
	v_mov_b32_e32 v41, v34
	v_mov_b32_e32 v42, v34
	v_mov_b32_e32 v43, v34
	v_mov_b32_e32 v44, v34
	v_mov_b32_e32 v45, v34
	v_mov_b32_e32 v46, v34
	v_mov_b32_e32 v47, v34
	v_mov_b32_e32 v48, v34
	v_mov_b32_e32 v49, v34
	v_sub_f32_e32 v2, v2, v237
	v_sub_f32_e32 v3, v3, v237
	s_waitcnt vmcnt(0) lgkmcnt(0)
	s_barrier
; #define WAIT_BAR(N) asm volatile("s_waitcnt vmcnt(" #N ") lgkmcnt(0)\n\ts_barrier":::"memory")
;   #define DMA_K(t,slot) glds16(ksrc+(long)(t)*KVBLK*KVP,(unsigned)__builtin_amdgcn_readfirstlane(kdst+(slot)))
;   #define DMA_V(t,slot) glds16(vsrc+(long)(t)*KVBLK*KVP,(unsigned)__builtin_amdgcn_readfirstlane(vdst+(slot)))
;   #define RESC() do{ if(resc){ asm volatile("s_waitcnt lgkmcnt(0)":::"memory"); \
;       _Pragma("unroll") for(int d_=0;d_<2;++d_) _Pragma("unroll") for(int r=0;r<16;++r)o[d_][r]*=wsf[crow(r,hi)]; } }while(0)
;   #define ROT() do{sl_prev=sl_cur;sl_cur=sl_next;sl_next=(sl_next==(NSLOT-1)*SLOTB)?0:sl_next+SLOTB;}while(0)
; template<int THRL> __device__ __forceinline__ void attn_unit(const bf16*Qu,const bf16*__restrict__ Kh,const bf16*__restrict__ Vh,bf16*Ou,const int NT,const float shift,char*shm){
;     ...
;   _Pragma("unroll") for(int r=0;r<16;++r)pA1[r]=__builtin_amdgcn_exp2f(pA1[r]);
;   WAIT_BAR(0);
;   DMA_K(3,0);DMA_V(1,SLOTB);
;   ROT();
;   kload8(kf,kp0+sl_cur);
;   WAIT_BAR(2);
;     ...
;   int t=1;
;     ...
;   for(;t+5<NT;t+=2){
;     STEP(pB0,pB1,pA0,pA1,t,true,true,true);     WAIT_BAR(2); RESC(); ROT();
;     STEP(pA0,pA1,pB0,pB1,t+1,true,true,true);   WAIT_BAR(2); RESC(); ROT();
	v_sub_f32_e32 v18, v18, v237
	v_sub_f32_e32 v19, v19, v237
	s_nop 0
	v_exp_f32_e32 v66, v2
	v_exp_f32_e32 v67, v3
	v_lshl_add_u64 v[2:3], v[212:213], 0, s[34:35]
	s_mov_b32 s6, m0
	s_mov_b32 m0, s70
	s_nop 0
	global_load_lds_dwordx4 v[2:3], off
	s_mov_b32 m0, s6
	v_lshl_add_u64 v[2:3], v[214:215], 0, s[26:27]
	s_add_i32 s6, s70, 0x8000
	s_mov_b32 s7, m0
	s_mov_b32 m0, s6
	s_nop 0
	global_load_lds_dwordx4 v[2:3], off
	s_mov_b32 m0, s7
	ds_read_b128 v[190:193], v244 offset:8192
	ds_read_b128 v[186:189], v244 offset:8704
	ds_read_b128 v[182:185], v244 offset:10240
	ds_read_b128 v[178:181], v244 offset:10752
	ds_read_b128 v[174:177], v244 offset:12288
	ds_read_b128 v[170:173], v244 offset:12800
	ds_read_b128 v[166:169], v244 offset:14336
	ds_read_b128 v[162:165], v244 offset:14848
	v_sub_f32_e32 v20, v20, v237
	v_sub_f32_e32 v4, v4, v237
	v_sub_f32_e32 v21, v21, v237
	v_sub_f32_e32 v5, v5, v237
	v_sub_f32_e32 v22, v22, v237
	v_sub_f32_e32 v6, v6, v237
	v_sub_f32_e32 v23, v23, v237
	v_sub_f32_e32 v7, v7, v237
	v_sub_f32_e32 v24, v24, v237
	v_sub_f32_e32 v8, v8, v237
	v_sub_f32_e32 v25, v25, v237
	v_sub_f32_e32 v9, v9, v237
	v_sub_f32_e32 v26, v26, v237
	v_sub_f32_e32 v10, v10, v237
	v_sub_f32_e32 v27, v27, v237
	v_sub_f32_e32 v11, v11, v237
	v_sub_f32_e32 v28, v28, v237
	v_sub_f32_e32 v12, v12, v237
	v_sub_f32_e32 v29, v29, v237
	v_sub_f32_e32 v13, v13, v237
	v_sub_f32_e32 v30, v30, v237
	v_sub_f32_e32 v14, v14, v237
	v_sub_f32_e32 v31, v31, v237
	v_sub_f32_e32 v15, v15, v237
	v_sub_f32_e32 v32, v32, v237
	v_sub_f32_e32 v16, v16, v237
	v_sub_f32_e32 v33, v33, v237
	v_sub_f32_e32 v17, v17, v237
	v_exp_f32_e32 v82, v18
	v_exp_f32_e32 v83, v19
	v_exp_f32_e32 v84, v20
	v_exp_f32_e32 v85, v21
	v_exp_f32_e32 v86, v22
	v_exp_f32_e32 v87, v23
	v_exp_f32_e32 v88, v24
	v_exp_f32_e32 v89, v25
	v_exp_f32_e32 v90, v26
	v_exp_f32_e32 v91, v27
	v_exp_f32_e32 v92, v28
	v_exp_f32_e32 v93, v29
	v_exp_f32_e32 v94, v30
	v_exp_f32_e32 v95, v31
	v_exp_f32_e32 v96, v32
	v_exp_f32_e32 v97, v33
	v_exp_f32_e32 v68, v4
	v_exp_f32_e32 v69, v5
	v_exp_f32_e32 v70, v6
	v_exp_f32_e32 v71, v7
	v_exp_f32_e32 v72, v8
	v_exp_f32_e32 v73, v9
	v_exp_f32_e32 v74, v10
	v_exp_f32_e32 v75, v11
	v_exp_f32_e32 v76, v12
	v_exp_f32_e32 v77, v13
	v_exp_f32_e32 v78, v14
	v_exp_f32_e32 v79, v15
	v_exp_f32_e32 v80, v16
	v_exp_f32_e32 v81, v17
	s_waitcnt vmcnt(2) lgkmcnt(0)
	s_barrier
	v_lshl_or_b32 v0, v241, 8, v0
	v_add3_u32 v245, v50, v242, v0
	s_cmp_lt_i32 s91, 7
	s_cbranch_scc1 .LBB0_620
	s_mov_b64 s[4:5], 0xa000
	v_add_u32_e32 v51, s24, v245
	v_mov_b32_e32 v50, 0
	v_mov_b32_e32 v194, 0
	v_mov_b32_e32 v195, 0
	v_mov_b32_e32 v196, 0
	v_lshlrev_b32_e32 v197, 4, v238
	v_readfirstlane_b32 s98, v212
	v_readfirstlane_b32 s99, v213
	v_readfirstlane_b32 s100, v214
	v_readfirstlane_b32 s101, v215
	s_add_u32 s98, s98, 0x8000
	s_addc_u32 s99, s99, 0
	s_add_u32 s100, s100, 0x4000
	s_addc_u32 s101, s101, 0
	s_mov_b32 s26, 6
	v_mov_b32_e32 v2, 0
	v_mov_b32_e32 v3, v50
	v_mov_b32_e32 v4, v50
	v_mov_b32_e32 v5, v50
	v_mov_b32_e32 v6, v50
	v_mov_b32_e32 v7, v50
	v_mov_b32_e32 v8, v50
	v_mov_b32_e32 v9, v50
	v_mov_b32_e32 v10, v50
	v_mov_b32_e32 v11, v50
	v_mov_b32_e32 v12, v50
	v_mov_b32_e32 v13, v50
	v_mov_b32_e32 v14, v50
	v_mov_b32_e32 v15, v50
	v_mov_b32_e32 v16, v50
	v_mov_b32_e32 v17, v50
	v_mov_b32_e32 v18, 0
	v_mov_b32_e32 v19, v50
	v_mov_b32_e32 v20, v50
	v_mov_b32_e32 v21, v50
	v_mov_b32_e32 v22, v50
	v_mov_b32_e32 v23, v50
	v_mov_b32_e32 v24, v50
	v_mov_b32_e32 v25, v50
	v_mov_b32_e32 v26, v50
	v_mov_b32_e32 v27, v50
	v_mov_b32_e32 v28, v50
	v_mov_b32_e32 v29, v50
	v_mov_b32_e32 v30, v50
	v_mov_b32_e32 v31, v50
	v_mov_b32_e32 v32, v50
	v_mov_b32_e32 v33, v50
	s_branch .LBB0_618
.Lattn_rot:
	s_waitcnt vmcnt(2) lgkmcnt(0)
	s_barrier
.LBB0_618:
	s_mov_b32 s4, s76
	s_mov_b32 s5, s26
	s_mov_b32 s25, s31
	ds_read_b64_tr_b16 v[52:53], v51 offset:24576
	ds_read_b64_tr_b16 v[54:55], v51 offset:25088
	s_waitcnt lgkmcnt(9)
	v_mfma_f32_32x32x16_bf16 v[114:129], v[190:193], v[150:153], v[34:49]
	v_add_f32_e32 v50, v82, v50
	v_add_f32_e32 v194, v83, v194
	v_add_f32_e32 v195, v84, v195
	v_add_f32_e32 v196, v85, v196
	v_add_f32_e32 v50, v86, v50
	v_add_f32_e32 v194, v87, v194
	v_cvt_pk_bf16_f32 v158, v82, v83
	v_cvt_pk_bf16_f32 v159, v84, v85
	ds_read_b64_tr_b16 v[60:61], v51 offset:28672
	ds_read_b64_tr_b16 v[62:63], v51 offset:29184
	s_waitcnt lgkmcnt(10)
	v_mfma_f32_32x32x16_bf16 v[98:113], v[186:189], v[150:153], v[34:49]
	v_add_f32_e32 v195, v88, v195
	v_add_f32_e32 v196, v89, v196
	v_add_f32_e32 v50, v90, v50
	v_add_f32_e32 v194, v91, v194
	v_cvt_pk_bf16_f32 v160, v86, v87
	v_cvt_pk_bf16_f32 v161, v88, v89
	ds_read_b64_tr_b16 v[82:83], v51 offset:25600
	ds_read_b64_tr_b16 v[84:85], v51 offset:26112
	s_waitcnt lgkmcnt(11)
	v_mfma_f32_32x32x16_bf16 v[114:129], v[182:185], v[138:141], v[114:129]
	v_add_f32_e32 v195, v92, v195
	v_add_f32_e32 v196, v93, v196
	v_add_f32_e32 v50, v94, v50
	v_add_f32_e32 v194, v95, v194
	v_cvt_pk_bf16_f32 v154, v90, v91
	v_cvt_pk_bf16_f32 v155, v92, v93
	ds_read_b64_tr_b16 v[86:87], v51 offset:29696
	ds_read_b64_tr_b16 v[88:89], v51 offset:30208
	s_waitcnt lgkmcnt(12)
	v_mfma_f32_32x32x16_bf16 v[98:113], v[178:181], v[138:141], v[98:113]
	v_add_f32_e32 v195, v96, v195
	v_add_f32_e32 v196, v97, v196
	v_add_f32_e32 v50, v66, v50
	v_add_f32_e32 v194, v67, v194
	v_cvt_pk_bf16_f32 v156, v94, v95
	v_cvt_pk_bf16_f32 v157, v96, v97
	ds_read_b64_tr_b16 v[90:91], v51 offset:26624
	ds_read_b64_tr_b16 v[92:93], v51 offset:27136
	s_waitcnt lgkmcnt(13)
; #define WAIT_BAR(N) asm volatile("s_waitcnt vmcnt(" #N ") lgkmcnt(0)\n\ts_barrier":::"memory")
;   #define RESC() do{ if(resc){ asm volatile("s_waitcnt lgkmcnt(0)":::"memory"); \
;       _Pragma("unroll") for(int d_=0;d_<2;++d_) _Pragma("unroll") for(int r=0;r<16;++r)o[d_][r]*=wsf[crow(r,hi)]; } }while(0)
;   #define ROT() do{sl_prev=sl_cur;sl_cur=sl_next;sl_next=(sl_next==(NSLOT-1)*SLOTB)?0:sl_next+SLOTB;}while(0)
; template<int THRL> __device__ __forceinline__ void attn_unit(const bf16*Qu,const bf16*__restrict__ Kh,const bf16*__restrict__ Vh,bf16*Ou,const int NT,const float shift,char*shm){
;     ...
;   int t=1;
;     ...
;   for(;t+5<NT;t+=2){
;     STEP(pB0,pB1,pA0,pA1,t,true,true,true);     WAIT_BAR(2); RESC(); ROT();
;     STEP(pA0,pA1,pB0,pB1,t+1,true,true,true);   WAIT_BAR(2); RESC(); ROT();
	v_mfma_f32_32x32x16_bf16 v[114:129], v[174:177], v[134:137], v[114:129]
	v_add_f32_e32 v195, v68, v195
	v_add_f32_e32 v196, v69, v196
	v_add_f32_e32 v50, v70, v50
	v_add_f32_e32 v194, v71, v194
	v_cvt_pk_bf16_f32 v146, v66, v67
	v_cvt_pk_bf16_f32 v147, v68, v69
	ds_read_b64_tr_b16 v[64:65], v51 offset:30720
	ds_read_b64_tr_b16 v[66:67], v51 offset:31232
	s_waitcnt lgkmcnt(14)
	v_mfma_f32_32x32x16_bf16 v[98:113], v[170:173], v[134:137], v[98:113]
	v_add_f32_e32 v195, v72, v195
	v_add_f32_e32 v196, v73, v196
	v_add_f32_e32 v50, v74, v50
	v_add_f32_e32 v194, v75, v194
	v_cvt_pk_bf16_f32 v148, v70, v71
	v_cvt_pk_bf16_f32 v149, v72, v73
	ds_read_b64_tr_b16 v[68:69], v51 offset:27648
	ds_read_b64_tr_b16 v[70:71], v51 offset:28160
	s_waitcnt lgkmcnt(14)
	v_mfma_f32_32x32x16_bf16 v[114:129], v[166:169], v[130:133], v[114:129]
	v_add_f32_e32 v195, v76, v195
	v_add_f32_e32 v196, v77, v196
	v_add_f32_e32 v50, v78, v50
	v_add_f32_e32 v194, v79, v194
	v_cvt_pk_bf16_f32 v142, v74, v75
	v_cvt_pk_bf16_f32 v143, v76, v77
	ds_read_b64_tr_b16 v[72:73], v51 offset:31744
	ds_read_b64_tr_b16 v[74:75], v51 offset:32256
	v_mfma_f32_32x32x16_bf16 v[98:113], v[162:165], v[130:133], v[98:113]
	v_add_f32_e32 v195, v80, v195
	v_add_f32_e32 v196, v81, v196
	v_cvt_pk_bf16_f32 v144, v78, v79
	v_cvt_pk_bf16_f32 v145, v80, v81
	s_add_i32 s6, s31, s70
	s_mov_b32 s7, m0
	s_mov_b32 m0, s6
	s_nop 0
	global_load_lds_dwordx4 v197, s[98:99]
	s_mov_b32 m0, s7
	s_add_i32 s6, s76, s71
	s_mov_b32 s7, m0
	s_mov_b32 m0, s6
	s_nop 0
	global_load_lds_dwordx4 v197, s[100:101]
	s_mov_b32 m0, s7
	s_add_u32 s98, s98, 0x2000
	s_addc_u32 s99, s99, 0
	s_add_u32 s100, s100, 0x2000
	s_addc_u32 s101, s101, 0
	s_waitcnt lgkmcnt(14)
	v_mfma_f32_32x32x16_bf16 v[2:17], v[158:161], v[52:55], v[2:17]
	v_exp_f32_e32 v114, v114
	v_exp_f32_e32 v115, v115
	v_exp_f32_e32 v116, v116
	v_exp_f32_e32 v117, v117
	s_waitcnt lgkmcnt(12)
	v_mfma_f32_32x32x16_bf16 v[18:33], v[158:161], v[60:63], v[18:33]
	v_exp_f32_e32 v118, v118
	v_exp_f32_e32 v119, v119
	v_exp_f32_e32 v120, v120
	v_exp_f32_e32 v121, v121
	v_add_u32_e32 v52, s4, v244
	v_add_u32_e32 v198, s25, v245
	ds_read_b128 v[60:63], v52
	ds_read_b128 v[162:165], v52 offset:512
	s_waitcnt lgkmcnt(12)
	v_mfma_f32_32x32x16_bf16 v[2:17], v[154:157], v[82:85], v[2:17]
	v_exp_f32_e32 v122, v122
	v_exp_f32_e32 v123, v123
	v_exp_f32_e32 v124, v124
	v_exp_f32_e32 v125, v125
	ds_read_b128 v[166:169], v52 offset:2048
	ds_read_b128 v[170:173], v52 offset:2560
	s_waitcnt lgkmcnt(12)
	v_mfma_f32_32x32x16_bf16 v[18:33], v[154:157], v[86:89], v[18:33]
	v_exp_f32_e32 v126, v126
	v_exp_f32_e32 v127, v127
	v_exp_f32_e32 v128, v128
	v_exp_f32_e32 v129, v129
	ds_read_b128 v[174:177], v52 offset:4096
	ds_read_b128 v[178:181], v52 offset:4608
	s_waitcnt lgkmcnt(12)
	v_mfma_f32_32x32x16_bf16 v[2:17], v[146:149], v[90:93], v[2:17]
	v_exp_f32_e32 v98, v98
	v_exp_f32_e32 v99, v99
	v_exp_f32_e32 v100, v100
	v_exp_f32_e32 v101, v101
	ds_read_b128 v[182:185], v52 offset:6144
	ds_read_b128 v[52:55], v52 offset:6656
	s_waitcnt lgkmcnt(12)
	v_mfma_f32_32x32x16_bf16 v[18:33], v[146:149], v[64:67], v[18:33]
	v_exp_f32_e32 v102, v102
	v_exp_f32_e32 v103, v103
	v_exp_f32_e32 v104, v104
	v_exp_f32_e32 v105, v105
	s_waitcnt lgkmcnt(10)
	v_mfma_f32_32x32x16_bf16 v[2:17], v[142:145], v[68:71], v[2:17]
	v_exp_f32_e32 v106, v106
	v_exp_f32_e32 v107, v107
	v_exp_f32_e32 v108, v108
	v_exp_f32_e32 v109, v109
	s_waitcnt lgkmcnt(8)
	v_mfma_f32_32x32x16_bf16 v[18:33], v[142:145], v[72:75], v[18:33]
	v_exp_f32_e32 v110, v110
	v_exp_f32_e32 v111, v111
	v_exp_f32_e32 v112, v112
	v_exp_f32_e32 v113, v113
	s_waitcnt vmcnt(2) lgkmcnt(0)
	s_barrier
; #define WAIT_BAR(N) asm volatile("s_waitcnt vmcnt(" #N ") lgkmcnt(0)\n\ts_barrier":::"memory")
;   #define RESC() do{ if(resc){ asm volatile("s_waitcnt lgkmcnt(0)":::"memory"); \
;       _Pragma("unroll") for(int d_=0;d_<2;++d_) _Pragma("unroll") for(int r=0;r<16;++r)o[d_][r]*=wsf[crow(r,hi)]; } }while(0)
;   #define ROT() do{sl_prev=sl_cur;sl_cur=sl_next;sl_next=(sl_next==(NSLOT-1)*SLOTB)?0:sl_next+SLOTB;}while(0)
; template<int THRL> __device__ __forceinline__ void attn_unit(const bf16*Qu,const bf16*__restrict__ Kh,const bf16*__restrict__ Vh,bf16*Ou,const int NT,const float shift,char*shm){
;     ...
;   int t=1;
;     ...
;   for(;t+5<NT;t+=2){
;     STEP(pB0,pB1,pA0,pA1,t,true,true,true);     WAIT_BAR(2); RESC(); ROT();
;     STEP(pA0,pA1,pB0,pB1,t+1,true,true,true);   WAIT_BAR(2); RESC(); ROT();
;   }
	s_add_i32 s6, s76, 0x2000
	s_cmpk_lg_i32 s76, 0x4000
	s_cselect_b32 s31, s6, 0
	ds_read_b64_tr_b16 v[186:187], v198 offset:24576
	ds_read_b64_tr_b16 v[188:189], v198 offset:25088
	s_waitcnt lgkmcnt(9)
	v_mfma_f32_32x32x16_bf16 v[82:97], v[60:63], v[150:153], v[34:49]
	v_add_f32_e32 v50, v114, v50
	v_add_f32_e32 v194, v115, v194
	v_add_f32_e32 v195, v116, v195
	v_add_f32_e32 v196, v117, v196
	v_add_f32_e32 v50, v118, v50
	v_add_f32_e32 v194, v119, v194
	v_cvt_pk_bf16_f32 v158, v114, v115
	v_cvt_pk_bf16_f32 v159, v116, v117
	ds_read_b64_tr_b16 v[60:61], v198 offset:28672
	ds_read_b64_tr_b16 v[62:63], v198 offset:29184
	s_waitcnt lgkmcnt(10)
	v_mfma_f32_32x32x16_bf16 v[66:81], v[162:165], v[150:153], v[34:49]
	v_add_f32_e32 v195, v120, v195
	v_add_f32_e32 v196, v121, v196
	v_add_f32_e32 v50, v122, v50
	v_add_f32_e32 v194, v123, v194
	v_cvt_pk_bf16_f32 v160, v118, v119
	v_cvt_pk_bf16_f32 v161, v120, v121
	ds_read_b64_tr_b16 v[114:115], v198 offset:25600
	ds_read_b64_tr_b16 v[116:117], v198 offset:26112
	s_waitcnt lgkmcnt(11)
	v_mfma_f32_32x32x16_bf16 v[82:97], v[166:169], v[138:141], v[82:97]
	v_add_f32_e32 v195, v124, v195
	v_add_f32_e32 v196, v125, v196
	v_add_f32_e32 v50, v126, v50
	v_add_f32_e32 v194, v127, v194
	v_cvt_pk_bf16_f32 v154, v122, v123
	v_cvt_pk_bf16_f32 v155, v124, v125
	ds_read_b64_tr_b16 v[118:119], v198 offset:29696
	ds_read_b64_tr_b16 v[120:121], v198 offset:30208
	s_waitcnt lgkmcnt(12)
	v_mfma_f32_32x32x16_bf16 v[66:81], v[170:173], v[138:141], v[66:81]
	v_add_f32_e32 v195, v128, v195
	v_add_f32_e32 v196, v129, v196
	v_add_f32_e32 v50, v98, v50
	v_add_f32_e32 v194, v99, v194
	v_cvt_pk_bf16_f32 v156, v126, v127
	v_cvt_pk_bf16_f32 v157, v128, v129
	ds_read_b64_tr_b16 v[122:123], v198 offset:26624
	ds_read_b64_tr_b16 v[124:125], v198 offset:27136
	s_waitcnt lgkmcnt(13)
	v_mfma_f32_32x32x16_bf16 v[82:97], v[174:177], v[134:137], v[82:97]
	v_add_f32_e32 v195, v100, v195
	v_add_f32_e32 v196, v101, v196
	v_add_f32_e32 v50, v102, v50
	v_add_f32_e32 v194, v103, v194
	v_cvt_pk_bf16_f32 v146, v98, v99
	v_cvt_pk_bf16_f32 v147, v100, v101
	ds_read_b64_tr_b16 v[98:99], v198 offset:30720
	ds_read_b64_tr_b16 v[100:101], v198 offset:31232
	s_waitcnt lgkmcnt(14)
	v_mfma_f32_32x32x16_bf16 v[66:81], v[178:181], v[134:137], v[66:81]
	v_add_f32_e32 v195, v104, v195
	v_add_f32_e32 v196, v105, v196
	v_add_f32_e32 v50, v106, v50
	v_add_f32_e32 v194, v107, v194
	v_cvt_pk_bf16_f32 v148, v102, v103
	v_cvt_pk_bf16_f32 v149, v104, v105
	ds_read_b64_tr_b16 v[102:103], v198 offset:27648
	ds_read_b64_tr_b16 v[104:105], v198 offset:28160
	s_waitcnt lgkmcnt(14)
	v_mfma_f32_32x32x16_bf16 v[82:97], v[182:185], v[130:133], v[82:97]
	v_add_f32_e32 v195, v108, v195
	v_add_f32_e32 v196, v109, v196
	v_add_f32_e32 v50, v110, v50
	v_add_f32_e32 v194, v111, v194
	v_cvt_pk_bf16_f32 v142, v106, v107
	v_cvt_pk_bf16_f32 v143, v108, v109
	ds_read_b64_tr_b16 v[106:107], v198 offset:31744
	ds_read_b64_tr_b16 v[108:109], v198 offset:32256
	v_mfma_f32_32x32x16_bf16 v[66:81], v[52:55], v[130:133], v[66:81]
	v_add_f32_e32 v195, v112, v195
	v_add_f32_e32 v196, v113, v196
	v_cvt_pk_bf16_f32 v144, v110, v111
	v_cvt_pk_bf16_f32 v145, v112, v113
	s_add_i32 s6, s76, s70
	s_mov_b32 s7, m0
	s_mov_b32 m0, s6
	s_nop 0
	global_load_lds_dwordx4 v197, s[98:99]
	s_mov_b32 m0, s7
	s_add_i32 s6, s31, s71
	s_mov_b32 s7, m0
	s_mov_b32 m0, s6
	s_nop 0
	global_load_lds_dwordx4 v197, s[100:101]
	s_mov_b32 m0, s7
	s_add_u32 s98, s98, 0x2000
	s_addc_u32 s99, s99, 0
	s_add_u32 s100, s100, 0x2000
	s_addc_u32 s101, s101, 0
	s_waitcnt lgkmcnt(14)
	v_mfma_f32_32x32x16_bf16 v[2:17], v[158:161], v[186:189], v[2:17]
	v_exp_f32_e32 v82, v82
	v_exp_f32_e32 v83, v83
	v_exp_f32_e32 v84, v84
	v_exp_f32_e32 v85, v85
	s_waitcnt lgkmcnt(12)
	v_mfma_f32_32x32x16_bf16 v[18:33], v[158:161], v[60:63], v[18:33]
	v_exp_f32_e32 v86, v86
	v_exp_f32_e32 v87, v87
	v_exp_f32_e32 v88, v88
	v_exp_f32_e32 v89, v89
	v_add_u32_e32 v53, s31, v244
	v_add_u32_e32 v51, s76, v245
	ds_read_b128 v[190:193], v53
	ds_read_b128 v[186:189], v53 offset:512
	s_waitcnt lgkmcnt(12)
	v_mfma_f32_32x32x16_bf16 v[2:17], v[154:157], v[114:117], v[2:17]
	v_exp_f32_e32 v90, v90
	v_exp_f32_e32 v91, v91
	v_exp_f32_e32 v92, v92
	v_exp_f32_e32 v93, v93
	ds_read_b128 v[182:185], v53 offset:2048
	ds_read_b128 v[178:181], v53 offset:2560
	s_waitcnt lgkmcnt(12)
	v_mfma_f32_32x32x16_bf16 v[18:33], v[154:157], v[118:121], v[18:33]
	v_exp_f32_e32 v94, v94
	v_exp_f32_e32 v95, v95
	v_exp_f32_e32 v96, v96
	v_exp_f32_e32 v97, v97
	ds_read_b128 v[174:177], v53 offset:4096
	ds_read_b128 v[170:173], v53 offset:4608
	s_waitcnt lgkmcnt(12)
	v_mfma_f32_32x32x16_bf16 v[2:17], v[146:149], v[122:125], v[2:17]
	v_exp_f32_e32 v66, v66
	v_exp_f32_e32 v67, v67
	v_exp_f32_e32 v68, v68
	v_exp_f32_e32 v69, v69
	ds_read_b128 v[166:169], v53 offset:6144
	ds_read_b128 v[162:165], v53 offset:6656
	s_waitcnt lgkmcnt(12)
	v_mfma_f32_32x32x16_bf16 v[18:33], v[146:149], v[98:101], v[18:33]
	v_exp_f32_e32 v70, v70
	v_exp_f32_e32 v71, v71
	v_exp_f32_e32 v72, v72
	v_exp_f32_e32 v73, v73
	s_waitcnt lgkmcnt(10)
	v_mfma_f32_32x32x16_bf16 v[2:17], v[142:145], v[102:105], v[2:17]
	v_exp_f32_e32 v74, v74
	v_exp_f32_e32 v75, v75
	v_exp_f32_e32 v76, v76
	v_exp_f32_e32 v77, v77
	s_waitcnt lgkmcnt(8)
	v_mfma_f32_32x32x16_bf16 v[18:33], v[142:145], v[106:109], v[18:33]
	v_exp_f32_e32 v78, v78
	v_exp_f32_e32 v79, v79
	v_exp_f32_e32 v80, v80
	v_exp_f32_e32 v81, v81
	s_add_i32 s6, s31, 0x2000
	s_cmpk_lg_i32 s31, 0x4000
	s_mov_b32 s24, s76
	s_cselect_b32 s76, s6, 0
	s_add_i32 s26, s26, 2
	s_cmp_ge_i32 s26, s91
	s_cbranch_scc0 .Lattn_rot
	s_waitcnt vmcnt(2) lgkmcnt(0)
	s_barrier
	v_add_f32_e32 v50, v50, v194
	v_add_f32_e32 v50, v50, v195
	v_add_f32_e32 v50, v50, v196
	s_add_i32 s5, s5, -3
	s_branch .LBB0_621
